# P6 EpiAct: hoist 8 SS1 loads to epilogue top, counted vmcnt(7) waits
# speedup vs baseline: 1.0059x; 1.0059x over previous
; __device__ __forceinline__ unsigned cvt_pk_bf16(float lo, float hi) { unsigned r; asm volatile("v_cvt_pk_bf16_f32 %0, %1, %2" : "=v"(r) : "v"(lo), "v"(hi)); return r; }
; #define LAS __attribute__((address_space(3)))
; __device__ __forceinline__ float siluf_(float x) { return x * __builtin_amdgcn_rcpf(1.0f + __builtin_amdgcn_exp2f(-1.4426950408889634f * x)); }
; __device__ __forceinline__ float rstd_of(float ss) { return __builtin_amdgcn_rsqf(ss * (1.0f / DM) + EPS); }
;     __device__ __forceinline__ void operator()(const pg8::f32x4 (&acc)[2][2][4][2], const Unit& u, int wr, int wc, int fr, int fq) const {
;         const int row0 = u.pm * BM + wr * 64, lane = fr + 16 * fq, rr = lane >> 2, sl = lane & 3;
;         LAS unsigned char* W = scr + (wr * 4 + wc) * 2048;
;         bf16* outp = ACT + (size_t)(row0 + rr) * DFF + u.pn * HALF + wc * 32 + sl * 8;
; #pragma unroll
;         for (int ai = 0; ai < 2; ++ai)
; #pragma unroll
;             for (int m = 0; m < 4; ++m) { const int rg = ai * HALF + m * 16; const float rs = rstd_of(SS1[row0 + rg + fr]);
;                 const pg8::f32x4 g0 = acc[ai][0][m][0] * rs, g1 = acc[ai][0][m][1] * rs, u0 = acc[ai][1][m][0] * rs, u1 = acc[ai][1][m][1] * rs;
;                 u32x4 w; w.x = cvt_pk_bf16(siluf_(g0[0]) * u0[0], siluf_(g0[1]) * u0[1]); w.y = cvt_pk_bf16(siluf_(g0[2]) * u0[2], siluf_(g0[3]) * u0[3]);
;                 w.z = cvt_pk_bf16(siluf_(g1[0]) * u1[0], siluf_(g1[1]) * u1[1]); w.w = cvt_pk_bf16(siluf_(g1[2]) * u1[2], siluf_(g1[3]) * u1[3]);
;                 *(LAS u32x4*)epi_slot(W, fr, fq + 4 * (m & 1)) = w;
;                 const u32x4 o = *(const LAS u32x4*)epi_slot(W, rr, sl + 4 * (m & 1));
;                 *(u32x4*)(outp + (size_t)rg * DFF) = o; }
.LBB0_880:
	s_lshl_b32 s4, s4, 8
	s_add_i32 s21, s4, s42
	v_or_b32_e32 v148, s21, v152
	v_ashrrev_i32_e32 v149, 31, v148
	v_lshl_add_u64 v[150:151], v[148:149], 2, s[14:15]
	global_load_dword v149, v[150:151], off
	global_load_dword v201, v[150:151], off offset:64
	global_load_dword v202, v[150:151], off offset:128
	global_load_dword v203, v[150:151], off offset:192
	global_load_dword v204, v[150:151], off offset:512
	global_load_dword v205, v[150:151], off offset:576
	global_load_dword v206, v[150:151], off offset:640
	global_load_dword v207, v[150:151], off offset:704
	v_mov_b64_e32 v[164:165], s[56:57]
	s_lshl_b32 s4, s5, 7
	s_ashr_i32 s5, s4, 31
	s_waitcnt vmcnt(7)
	v_fmamk_f32 v149, v149, 0x3a800000, v159
	v_rsq_f32_e32 v166, v149
	v_or_b32_e32 v149, s21, v153
	v_pk_mul_f32 v[124:125], v[124:125], v[166:167] op_sel_hi:[1,0]
	v_pk_mul_f32 v[128:129], v[128:129], v[166:167] op_sel_hi:[1,0]
	v_pk_mul_f32 v[126:127], v[126:127], v[166:167] op_sel_hi:[1,0]
	v_pk_mul_f32 v[122:123], v[122:123], v[166:167] op_sel_hi:[1,0]
	v_mul_f32_e32 v173, 0xbfb8aa3b, v125
	v_pk_mul_f32 v[120:121], v[120:121], v[166:167] op_sel_hi:[1,0]
	v_pk_mul_f32 v[118:119], v[118:119], v[166:167] op_sel_hi:[1,0]
	v_pk_mul_f32 v[116:117], v[116:117], v[166:167] op_sel_hi:[1,0]
	v_pk_mul_f32 v[114:115], v[114:115], v[166:167] op_sel_hi:[1,0]
	v_mul_f32_e32 v166, 0xbfb8aa3b, v126
	v_mul_f32_e32 v167, 0xbfb8aa3b, v127
	v_mul_f32_e32 v168, 0xbfb8aa3b, v128
	v_mul_f32_e32 v169, 0xbfb8aa3b, v129
	v_mul_f32_e32 v170, 0xbfb8aa3b, v122
	v_mul_f32_e32 v171, 0xbfb8aa3b, v123
	v_mul_f32_e32 v172, 0xbfb8aa3b, v124
	v_exp_f32_e32 v173, v173
	v_exp_f32_e32 v166, v166
	v_exp_f32_e32 v167, v167
	v_exp_f32_e32 v168, v168
	v_exp_f32_e32 v169, v169
	v_exp_f32_e32 v170, v170
	v_exp_f32_e32 v171, v171
	v_exp_f32_e32 v172, v172
	v_add_f32_e32 v173, 1.0, v173
	v_add_f32_e32 v166, 1.0, v166
	v_add_f32_e32 v167, 1.0, v167
	v_add_f32_e32 v168, 1.0, v168
	v_add_f32_e32 v169, 1.0, v169
	v_add_f32_e32 v170, 1.0, v170
	v_add_f32_e32 v171, 1.0, v171
	v_add_f32_e32 v172, 1.0, v172
	v_rcp_f32_e32 v173, v173
	v_rcp_f32_e32 v166, v166
	v_rcp_f32_e32 v167, v167
	v_rcp_f32_e32 v168, v168
	v_rcp_f32_e32 v169, v169
	v_rcp_f32_e32 v170, v170
	v_rcp_f32_e32 v171, v171
	v_rcp_f32_e32 v172, v172
	v_mul_f32_e32 v125, v125, v173
	v_mul_f32_e32 v126, v126, v166
	v_mul_f32_e32 v127, v127, v167
	v_mul_f32_e32 v128, v128, v168
	v_mul_f32_e32 v129, v129, v169
	v_mul_f32_e32 v122, v122, v170
	v_mul_f32_e32 v123, v123, v171
	v_mul_f32_e32 v124, v124, v172
	v_mul_f32_e32 v117, v117, v125
	v_mul_f32_e32 v118, v118, v126
	v_mul_f32_e32 v119, v119, v127
	v_mul_f32_e32 v120, v120, v128
	v_mul_f32_e32 v121, v121, v129
	v_mul_f32_e32 v122, v114, v122
	v_mul_f32_e32 v123, v115, v123
	v_mul_f32_e32 v124, v116, v124
	v_cvt_pk_bf16_f32 v114, v118, v119
	v_cvt_pk_bf16_f32 v115, v120, v121
	v_cvt_pk_bf16_f32 v116, v122, v123
	v_cvt_pk_bf16_f32 v117, v124, v117
	ds_write_b128 v160, v[114:117]
	ds_read_b128 v[116:119], v161
	v_mad_i64_i32 v[114:115], s[28:29], v149, s55, v[164:165]
	v_lshl_add_u64 v[114:115], s[4:5], 1, v[114:115]
	v_lshl_add_u64 v[114:115], v[114:115], 0, s[6:7]
	v_lshl_add_u64 v[114:115], v[114:115], 0, v[138:139]
	s_waitcnt lgkmcnt(0)
	global_store_dwordx4 v[114:115], v[116:119], off
	s_nop 1
	s_waitcnt vmcnt(7)
	v_fmamk_f32 v116, v201, 0x3a800000, v159
	v_rsq_f32_e32 v116, v116
	s_nop 0
	v_pk_mul_f32 v[108:109], v[108:109], v[116:117] op_sel_hi:[1,0]
	v_pk_mul_f32 v[112:113], v[112:113], v[116:117] op_sel_hi:[1,0]
	v_pk_mul_f32 v[110:111], v[110:111], v[116:117] op_sel_hi:[1,0]
	v_pk_mul_f32 v[106:107], v[106:107], v[116:117] op_sel_hi:[1,0]
	v_mul_f32_e32 v123, 0xbfb8aa3b, v109
	v_pk_mul_f32 v[104:105], v[104:105], v[116:117] op_sel_hi:[1,0]
	v_pk_mul_f32 v[102:103], v[102:103], v[116:117] op_sel_hi:[1,0]
	v_pk_mul_f32 v[100:101], v[100:101], v[116:117] op_sel_hi:[1,0]
	v_pk_mul_f32 v[98:99], v[98:99], v[116:117] op_sel_hi:[1,0]
	v_mul_f32_e32 v116, 0xbfb8aa3b, v110
	v_mul_f32_e32 v117, 0xbfb8aa3b, v111
	v_mul_f32_e32 v118, 0xbfb8aa3b, v112
	v_mul_f32_e32 v119, 0xbfb8aa3b, v113
	v_mul_f32_e32 v120, 0xbfb8aa3b, v106
	v_mul_f32_e32 v121, 0xbfb8aa3b, v107
	v_mul_f32_e32 v122, 0xbfb8aa3b, v108
	v_exp_f32_e32 v123, v123
	v_exp_f32_e32 v116, v116
	v_exp_f32_e32 v117, v117
	v_exp_f32_e32 v118, v118
	v_exp_f32_e32 v119, v119
	v_exp_f32_e32 v120, v120
	v_exp_f32_e32 v121, v121
	v_exp_f32_e32 v122, v122
	v_add_f32_e32 v123, 1.0, v123
	v_add_f32_e32 v116, 1.0, v116
	v_add_f32_e32 v117, 1.0, v117
	v_add_f32_e32 v118, 1.0, v118
	v_add_f32_e32 v119, 1.0, v119
	v_add_f32_e32 v120, 1.0, v120
	v_add_f32_e32 v121, 1.0, v121
	v_add_f32_e32 v122, 1.0, v122
	v_rcp_f32_e32 v123, v123
	v_rcp_f32_e32 v116, v116
	v_rcp_f32_e32 v117, v117
	v_rcp_f32_e32 v118, v118
	v_rcp_f32_e32 v119, v119
	v_rcp_f32_e32 v120, v120
	v_rcp_f32_e32 v121, v121
	v_rcp_f32_e32 v122, v122
	v_mul_f32_e32 v109, v109, v123
	v_mul_f32_e32 v110, v110, v116
	v_mul_f32_e32 v111, v111, v117
	v_mul_f32_e32 v112, v112, v118
	v_mul_f32_e32 v113, v113, v119
	v_mul_f32_e32 v106, v106, v120
	v_mul_f32_e32 v107, v107, v121
	v_mul_f32_e32 v108, v108, v122
	v_mul_f32_e32 v101, v101, v109
	v_mul_f32_e32 v102, v102, v110
	v_mul_f32_e32 v103, v103, v111
	v_mul_f32_e32 v104, v104, v112
	v_mul_f32_e32 v105, v105, v113
	v_mul_f32_e32 v106, v98, v106
	v_mul_f32_e32 v107, v99, v107
	v_mul_f32_e32 v108, v100, v108
	v_cvt_pk_bf16_f32 v98, v102, v103
	v_cvt_pk_bf16_f32 v99, v104, v105
	v_cvt_pk_bf16_f32 v100, v106, v107
	v_cvt_pk_bf16_f32 v101, v108, v101
	ds_write_b128 v162, v[98:101]
	ds_read_b128 v[98:101], v163
	v_add_co_u32_e32 v102, vcc, s41, v114
	s_nop 1
	v_addc_co_u32_e32 v103, vcc, 0, v115, vcc
	s_waitcnt lgkmcnt(0)
; __device__ __forceinline__ unsigned cvt_pk_bf16(float lo, float hi) { unsigned r; asm volatile("v_cvt_pk_bf16_f32 %0, %1, %2" : "=v"(r) : "v"(lo), "v"(hi)); return r; }
; #define LAS __attribute__((address_space(3)))
; __device__ __forceinline__ float siluf_(float x) { return x * __builtin_amdgcn_rcpf(1.0f + __builtin_amdgcn_exp2f(-1.4426950408889634f * x)); }
; __device__ __forceinline__ float rstd_of(float ss) { return __builtin_amdgcn_rsqf(ss * (1.0f / DM) + EPS); }
;     __device__ __forceinline__ void operator()(const pg8::f32x4 (&acc)[2][2][4][2], const Unit& u, int wr, int wc, int fr, int fq) const {
;     ...
;             for (int m = 0; m < 4; ++m) { const int rg = ai * HALF + m * 16; const float rs = rstd_of(SS1[row0 + rg + fr]);
;                 const pg8::f32x4 g0 = acc[ai][0][m][0] * rs, g1 = acc[ai][0][m][1] * rs, u0 = acc[ai][1][m][0] * rs, u1 = acc[ai][1][m][1] * rs;
;                 u32x4 w; w.x = cvt_pk_bf16(siluf_(g0[0]) * u0[0], siluf_(g0[1]) * u0[1]); w.y = cvt_pk_bf16(siluf_(g0[2]) * u0[2], siluf_(g0[3]) * u0[3]);
;                 w.z = cvt_pk_bf16(siluf_(g1[0]) * u1[0], siluf_(g1[1]) * u1[1]); w.w = cvt_pk_bf16(siluf_(g1[2]) * u1[2], siluf_(g1[3]) * u1[3]);
;                 *(LAS u32x4*)epi_slot(W, fr, fq + 4 * (m & 1)) = w;
;                 const u32x4 o = *(const LAS u32x4*)epi_slot(W, rr, sl + 4 * (m & 1));
;                 *(u32x4*)(outp + (size_t)rg * DFF) = o; }
	global_store_dwordx4 v[102:103], v[98:101], off
	s_nop 1
	s_waitcnt vmcnt(7)
	v_fmamk_f32 v98, v202, 0x3a800000, v159
	v_rsq_f32_e32 v98, v98
	s_nop 0
	v_pk_mul_f32 v[92:93], v[92:93], v[98:99] op_sel_hi:[1,0]
	v_pk_mul_f32 v[96:97], v[96:97], v[98:99] op_sel_hi:[1,0]
	v_pk_mul_f32 v[94:95], v[94:95], v[98:99] op_sel_hi:[1,0]
	v_pk_mul_f32 v[90:91], v[90:91], v[98:99] op_sel_hi:[1,0]
	v_mul_f32_e32 v105, 0xbfb8aa3b, v93
	v_pk_mul_f32 v[88:89], v[88:89], v[98:99] op_sel_hi:[1,0]
	v_pk_mul_f32 v[86:87], v[86:87], v[98:99] op_sel_hi:[1,0]
	v_pk_mul_f32 v[84:85], v[84:85], v[98:99] op_sel_hi:[1,0]
	v_pk_mul_f32 v[82:83], v[82:83], v[98:99] op_sel_hi:[1,0]
	v_mul_f32_e32 v98, 0xbfb8aa3b, v94
	v_mul_f32_e32 v99, 0xbfb8aa3b, v95
	v_mul_f32_e32 v100, 0xbfb8aa3b, v96
	v_mul_f32_e32 v101, 0xbfb8aa3b, v97
	v_mul_f32_e32 v102, 0xbfb8aa3b, v90
	v_mul_f32_e32 v103, 0xbfb8aa3b, v91
	v_mul_f32_e32 v104, 0xbfb8aa3b, v92
	v_exp_f32_e32 v105, v105
	v_exp_f32_e32 v98, v98
	v_exp_f32_e32 v99, v99
	v_exp_f32_e32 v100, v100
	v_exp_f32_e32 v101, v101
	v_exp_f32_e32 v102, v102
	v_exp_f32_e32 v103, v103
	v_exp_f32_e32 v104, v104
	v_add_f32_e32 v105, 1.0, v105
	v_add_f32_e32 v98, 1.0, v98
	v_add_f32_e32 v99, 1.0, v99
	v_add_f32_e32 v100, 1.0, v100
	v_add_f32_e32 v101, 1.0, v101
	v_add_f32_e32 v102, 1.0, v102
	v_add_f32_e32 v103, 1.0, v103
	v_add_f32_e32 v104, 1.0, v104
	v_rcp_f32_e32 v105, v105
	v_rcp_f32_e32 v98, v98
	v_rcp_f32_e32 v99, v99
	v_rcp_f32_e32 v100, v100
	v_rcp_f32_e32 v101, v101
	v_rcp_f32_e32 v102, v102
	v_rcp_f32_e32 v103, v103
	v_rcp_f32_e32 v104, v104
	v_mul_f32_e32 v93, v93, v105
	v_mul_f32_e32 v94, v94, v98
	v_mul_f32_e32 v95, v95, v99
	v_mul_f32_e32 v96, v96, v100
	v_mul_f32_e32 v97, v97, v101
	v_mul_f32_e32 v90, v90, v102
	v_mul_f32_e32 v91, v91, v103
	v_mul_f32_e32 v92, v92, v104
	v_mul_f32_e32 v85, v85, v93
	v_mul_f32_e32 v86, v86, v94
	v_mul_f32_e32 v87, v87, v95
	v_mul_f32_e32 v88, v88, v96
	v_mul_f32_e32 v89, v89, v97
	v_mul_f32_e32 v90, v82, v90
	v_mul_f32_e32 v91, v83, v91
	v_mul_f32_e32 v92, v84, v92
	v_cvt_pk_bf16_f32 v82, v86, v87
	v_cvt_pk_bf16_f32 v83, v88, v89
	v_cvt_pk_bf16_f32 v84, v90, v91
	v_cvt_pk_bf16_f32 v85, v92, v85
	ds_write_b128 v160, v[82:85]
	ds_read_b128 v[82:85], v161
	v_add_co_u32_e32 v86, vcc, s58, v114
	s_nop 1
	v_addc_co_u32_e32 v87, vcc, 0, v115, vcc
	s_waitcnt lgkmcnt(0)
	global_store_dwordx4 v[86:87], v[82:85], off
	s_nop 1
	s_waitcnt vmcnt(7)
	v_fmamk_f32 v82, v203, 0x3a800000, v159
	v_rsq_f32_e32 v82, v82
	s_nop 0
	v_pk_mul_f32 v[76:77], v[76:77], v[82:83] op_sel_hi:[1,0]
	v_pk_mul_f32 v[80:81], v[80:81], v[82:83] op_sel_hi:[1,0]
	v_pk_mul_f32 v[78:79], v[78:79], v[82:83] op_sel_hi:[1,0]
	v_pk_mul_f32 v[74:75], v[74:75], v[82:83] op_sel_hi:[1,0]
	v_mul_f32_e32 v91, 0xbfb8aa3b, v77
	v_pk_mul_f32 v[72:73], v[72:73], v[82:83] op_sel_hi:[1,0]
	v_pk_mul_f32 v[70:71], v[70:71], v[82:83] op_sel_hi:[1,0]
	v_pk_mul_f32 v[68:69], v[68:69], v[82:83] op_sel_hi:[1,0]
	v_pk_mul_f32 v[66:67], v[66:67], v[82:83] op_sel_hi:[1,0]
	v_mul_f32_e32 v82, 0xbfb8aa3b, v78
	v_mul_f32_e32 v83, 0xbfb8aa3b, v79
	v_mul_f32_e32 v86, 0xbfb8aa3b, v80
	v_mul_f32_e32 v87, 0xbfb8aa3b, v81
	v_mul_f32_e32 v88, 0xbfb8aa3b, v74
	v_mul_f32_e32 v89, 0xbfb8aa3b, v75
	v_mul_f32_e32 v90, 0xbfb8aa3b, v76
	v_exp_f32_e32 v91, v91
	v_exp_f32_e32 v82, v82
	v_exp_f32_e32 v83, v83
	v_exp_f32_e32 v86, v86
	v_exp_f32_e32 v87, v87
	v_exp_f32_e32 v88, v88
	v_exp_f32_e32 v89, v89
	v_exp_f32_e32 v90, v90
	v_add_f32_e32 v91, 1.0, v91
	v_add_f32_e32 v82, 1.0, v82
	v_add_f32_e32 v83, 1.0, v83
	v_add_f32_e32 v86, 1.0, v86
	v_add_f32_e32 v87, 1.0, v87
	v_add_f32_e32 v88, 1.0, v88
	v_add_f32_e32 v89, 1.0, v89
	v_add_f32_e32 v90, 1.0, v90
	v_rcp_f32_e32 v91, v91
	v_rcp_f32_e32 v82, v82
	v_rcp_f32_e32 v83, v83
	v_rcp_f32_e32 v86, v86
	v_rcp_f32_e32 v87, v87
	v_rcp_f32_e32 v88, v88
	v_rcp_f32_e32 v89, v89
	v_rcp_f32_e32 v90, v90
	v_mul_f32_e32 v77, v77, v91
	v_mul_f32_e32 v78, v78, v82
	v_mul_f32_e32 v79, v79, v83
	v_mul_f32_e32 v80, v80, v86
	v_mul_f32_e32 v81, v81, v87
	v_mul_f32_e32 v74, v74, v88
	v_mul_f32_e32 v75, v75, v89
	v_mul_f32_e32 v76, v76, v90
	v_mul_f32_e32 v69, v69, v77
	v_mul_f32_e32 v70, v70, v78
	v_mul_f32_e32 v71, v71, v79
	v_mul_f32_e32 v72, v72, v80
	v_mul_f32_e32 v73, v73, v81
	v_mul_f32_e32 v74, v66, v74
	v_mul_f32_e32 v75, v67, v75
	v_mul_f32_e32 v76, v68, v76
	v_cvt_pk_bf16_f32 v66, v70, v71
	v_cvt_pk_bf16_f32 v67, v72, v73
	v_cvt_pk_bf16_f32 v68, v74, v75
	v_cvt_pk_bf16_f32 v69, v76, v69
	ds_write_b128 v162, v[66:69]
	ds_read_b128 v[66:69], v163
	v_add_co_u32_e32 v70, vcc, s59, v114
	s_nop 1
	v_addc_co_u32_e32 v71, vcc, 0, v115, vcc
	s_waitcnt lgkmcnt(0)
	global_store_dwordx4 v[70:71], v[66:69], off
	s_nop 1
	s_waitcnt vmcnt(7)
; __device__ __forceinline__ unsigned cvt_pk_bf16(float lo, float hi) { unsigned r; asm volatile("v_cvt_pk_bf16_f32 %0, %1, %2" : "=v"(r) : "v"(lo), "v"(hi)); return r; }
; #define LAS __attribute__((address_space(3)))
; __device__ __forceinline__ float siluf_(float x) { return x * __builtin_amdgcn_rcpf(1.0f + __builtin_amdgcn_exp2f(-1.4426950408889634f * x)); }
; __device__ __forceinline__ float rstd_of(float ss) { return __builtin_amdgcn_rsqf(ss * (1.0f / DM) + EPS); }
;     __device__ __forceinline__ void operator()(const pg8::f32x4 (&acc)[2][2][4][2], const Unit& u, int wr, int wc, int fr, int fq) const {
;     ...
;             for (int m = 0; m < 4; ++m) { const int rg = ai * HALF + m * 16; const float rs = rstd_of(SS1[row0 + rg + fr]);
;                 const pg8::f32x4 g0 = acc[ai][0][m][0] * rs, g1 = acc[ai][0][m][1] * rs, u0 = acc[ai][1][m][0] * rs, u1 = acc[ai][1][m][1] * rs;
;                 u32x4 w; w.x = cvt_pk_bf16(siluf_(g0[0]) * u0[0], siluf_(g0[1]) * u0[1]); w.y = cvt_pk_bf16(siluf_(g0[2]) * u0[2], siluf_(g0[3]) * u0[3]);
;                 w.z = cvt_pk_bf16(siluf_(g1[0]) * u1[0], siluf_(g1[1]) * u1[1]); w.w = cvt_pk_bf16(siluf_(g1[2]) * u1[2], siluf_(g1[3]) * u1[3]);
;                 *(LAS u32x4*)epi_slot(W, fr, fq + 4 * (m & 1)) = w;
;                 const u32x4 o = *(const LAS u32x4*)epi_slot(W, rr, sl + 4 * (m & 1));
;                 *(u32x4*)(outp + (size_t)rg * DFF) = o; }
	v_fmamk_f32 v66, v204, 0x3a800000, v159
	v_rsq_f32_e32 v66, v66
	s_nop 0
	v_pk_mul_f32 v[60:61], v[60:61], v[66:67] op_sel_hi:[1,0]
	v_pk_mul_f32 v[64:65], v[64:65], v[66:67] op_sel_hi:[1,0]
	v_pk_mul_f32 v[62:63], v[62:63], v[66:67] op_sel_hi:[1,0]
	v_pk_mul_f32 v[58:59], v[58:59], v[66:67] op_sel_hi:[1,0]
	v_mul_f32_e32 v75, 0xbfb8aa3b, v61
	v_pk_mul_f32 v[56:57], v[56:57], v[66:67] op_sel_hi:[1,0]
	v_pk_mul_f32 v[54:55], v[54:55], v[66:67] op_sel_hi:[1,0]
	v_pk_mul_f32 v[52:53], v[52:53], v[66:67] op_sel_hi:[1,0]
	v_pk_mul_f32 v[50:51], v[50:51], v[66:67] op_sel_hi:[1,0]
	v_mul_f32_e32 v66, 0xbfb8aa3b, v62
	v_mul_f32_e32 v67, 0xbfb8aa3b, v63
	v_mul_f32_e32 v70, 0xbfb8aa3b, v64
	v_mul_f32_e32 v71, 0xbfb8aa3b, v65
	v_mul_f32_e32 v72, 0xbfb8aa3b, v58
	v_mul_f32_e32 v73, 0xbfb8aa3b, v59
	v_mul_f32_e32 v74, 0xbfb8aa3b, v60
	v_exp_f32_e32 v75, v75
	v_exp_f32_e32 v66, v66
	v_exp_f32_e32 v67, v67
	v_exp_f32_e32 v70, v70
	v_exp_f32_e32 v71, v71
	v_exp_f32_e32 v72, v72
	v_exp_f32_e32 v73, v73
	v_exp_f32_e32 v74, v74
	v_add_f32_e32 v75, 1.0, v75
	v_add_f32_e32 v66, 1.0, v66
	v_add_f32_e32 v67, 1.0, v67
	v_add_f32_e32 v70, 1.0, v70
	v_add_f32_e32 v71, 1.0, v71
	v_add_f32_e32 v72, 1.0, v72
	v_add_f32_e32 v73, 1.0, v73
	v_add_f32_e32 v74, 1.0, v74
	v_rcp_f32_e32 v75, v75
	v_rcp_f32_e32 v66, v66
	v_rcp_f32_e32 v67, v67
	v_rcp_f32_e32 v70, v70
	v_rcp_f32_e32 v71, v71
	v_rcp_f32_e32 v72, v72
	v_rcp_f32_e32 v73, v73
	v_rcp_f32_e32 v74, v74
	v_mul_f32_e32 v61, v61, v75
	v_mul_f32_e32 v62, v62, v66
	v_mul_f32_e32 v63, v63, v67
	v_mul_f32_e32 v64, v64, v70
	v_mul_f32_e32 v65, v65, v71
	v_mul_f32_e32 v58, v58, v72
	v_mul_f32_e32 v59, v59, v73
	v_mul_f32_e32 v60, v60, v74
	v_mul_f32_e32 v53, v53, v61
	v_mul_f32_e32 v54, v54, v62
	v_mul_f32_e32 v55, v55, v63
	v_mul_f32_e32 v56, v56, v64
	v_mul_f32_e32 v57, v57, v65
	v_mul_f32_e32 v58, v50, v58
	v_mul_f32_e32 v59, v51, v59
	v_mul_f32_e32 v60, v52, v60
	v_cvt_pk_bf16_f32 v50, v54, v55
	v_cvt_pk_bf16_f32 v51, v56, v57
	v_cvt_pk_bf16_f32 v52, v58, v59
	v_cvt_pk_bf16_f32 v53, v60, v53
	ds_write_b128 v160, v[50:53]
	ds_read_b128 v[50:53], v161
	v_add_co_u32_e32 v54, vcc, s60, v114
	s_nop 1
	v_addc_co_u32_e32 v55, vcc, 0, v115, vcc
	s_waitcnt lgkmcnt(0)
	global_store_dwordx4 v[54:55], v[50:53], off
	s_nop 1
	s_waitcnt vmcnt(7)
	v_fmamk_f32 v50, v205, 0x3a800000, v159
	v_rsq_f32_e32 v50, v50
	s_nop 0
	v_pk_mul_f32 v[44:45], v[44:45], v[50:51] op_sel_hi:[1,0]
	v_pk_mul_f32 v[48:49], v[48:49], v[50:51] op_sel_hi:[1,0]
	v_pk_mul_f32 v[46:47], v[46:47], v[50:51] op_sel_hi:[1,0]
	v_pk_mul_f32 v[42:43], v[42:43], v[50:51] op_sel_hi:[1,0]
	v_mul_f32_e32 v59, 0xbfb8aa3b, v45
	v_pk_mul_f32 v[40:41], v[40:41], v[50:51] op_sel_hi:[1,0]
	v_pk_mul_f32 v[38:39], v[38:39], v[50:51] op_sel_hi:[1,0]
	v_pk_mul_f32 v[36:37], v[36:37], v[50:51] op_sel_hi:[1,0]
	v_pk_mul_f32 v[34:35], v[34:35], v[50:51] op_sel_hi:[1,0]
	v_mul_f32_e32 v50, 0xbfb8aa3b, v46
	v_mul_f32_e32 v51, 0xbfb8aa3b, v47
	v_mul_f32_e32 v54, 0xbfb8aa3b, v48
	v_mul_f32_e32 v55, 0xbfb8aa3b, v49
	v_mul_f32_e32 v56, 0xbfb8aa3b, v42
	v_mul_f32_e32 v57, 0xbfb8aa3b, v43
	v_mul_f32_e32 v58, 0xbfb8aa3b, v44
	v_exp_f32_e32 v59, v59
	v_exp_f32_e32 v50, v50
	v_exp_f32_e32 v51, v51
	v_exp_f32_e32 v54, v54
	v_exp_f32_e32 v55, v55
	v_exp_f32_e32 v56, v56
	v_exp_f32_e32 v57, v57
	v_exp_f32_e32 v58, v58
	v_add_f32_e32 v59, 1.0, v59
	v_add_f32_e32 v50, 1.0, v50
	v_add_f32_e32 v51, 1.0, v51
	v_add_f32_e32 v54, 1.0, v54
	v_add_f32_e32 v55, 1.0, v55
	v_add_f32_e32 v56, 1.0, v56
	v_add_f32_e32 v57, 1.0, v57
	v_add_f32_e32 v58, 1.0, v58
	v_rcp_f32_e32 v59, v59
	v_rcp_f32_e32 v50, v50
	v_rcp_f32_e32 v51, v51
	v_rcp_f32_e32 v54, v54
	v_rcp_f32_e32 v55, v55
	v_rcp_f32_e32 v56, v56
	v_rcp_f32_e32 v57, v57
	v_rcp_f32_e32 v58, v58
	v_mul_f32_e32 v45, v45, v59
	v_mul_f32_e32 v46, v46, v50
	v_mul_f32_e32 v47, v47, v51
	v_mul_f32_e32 v48, v48, v54
	v_mul_f32_e32 v49, v49, v55
	v_mul_f32_e32 v42, v42, v56
	v_mul_f32_e32 v43, v43, v57
	v_mul_f32_e32 v44, v44, v58
	v_mul_f32_e32 v37, v37, v45
	v_mul_f32_e32 v38, v38, v46
	v_mul_f32_e32 v39, v39, v47
	v_mul_f32_e32 v40, v40, v48
	v_mul_f32_e32 v41, v41, v49
	v_mul_f32_e32 v42, v34, v42
	v_mul_f32_e32 v43, v35, v43
	v_mul_f32_e32 v44, v36, v44
	v_cvt_pk_bf16_f32 v34, v38, v39
	v_cvt_pk_bf16_f32 v35, v40, v41
	v_cvt_pk_bf16_f32 v36, v42, v43
	v_cvt_pk_bf16_f32 v37, v44, v37
	ds_write_b128 v162, v[34:37]
	ds_read_b128 v[34:37], v163
	v_add_co_u32_e32 v38, vcc, s61, v114
	s_nop 1
	v_addc_co_u32_e32 v39, vcc, 0, v115, vcc
	s_waitcnt lgkmcnt(0)
	global_store_dwordx4 v[38:39], v[34:37], off
	s_nop 1
	s_waitcnt vmcnt(7)
; __device__ __forceinline__ unsigned cvt_pk_bf16(float lo, float hi) { unsigned r; asm volatile("v_cvt_pk_bf16_f32 %0, %1, %2" : "=v"(r) : "v"(lo), "v"(hi)); return r; }
; #define LAS __attribute__((address_space(3)))
; __device__ __forceinline__ float siluf_(float x) { return x * __builtin_amdgcn_rcpf(1.0f + __builtin_amdgcn_exp2f(-1.4426950408889634f * x)); }
; __device__ __forceinline__ float rstd_of(float ss) { return __builtin_amdgcn_rsqf(ss * (1.0f / DM) + EPS); }
;     __device__ __forceinline__ void operator()(const pg8::f32x4 (&acc)[2][2][4][2], const Unit& u, int wr, int wc, int fr, int fq) const {
;     ...
;             for (int m = 0; m < 4; ++m) { const int rg = ai * HALF + m * 16; const float rs = rstd_of(SS1[row0 + rg + fr]);
;                 const pg8::f32x4 g0 = acc[ai][0][m][0] * rs, g1 = acc[ai][0][m][1] * rs, u0 = acc[ai][1][m][0] * rs, u1 = acc[ai][1][m][1] * rs;
;                 u32x4 w; w.x = cvt_pk_bf16(siluf_(g0[0]) * u0[0], siluf_(g0[1]) * u0[1]); w.y = cvt_pk_bf16(siluf_(g0[2]) * u0[2], siluf_(g0[3]) * u0[3]);
;                 w.z = cvt_pk_bf16(siluf_(g1[0]) * u1[0], siluf_(g1[1]) * u1[1]); w.w = cvt_pk_bf16(siluf_(g1[2]) * u1[2], siluf_(g1[3]) * u1[3]);
;                 *(LAS u32x4*)epi_slot(W, fr, fq + 4 * (m & 1)) = w;
;                 const u32x4 o = *(const LAS u32x4*)epi_slot(W, rr, sl + 4 * (m & 1));
;                 *(u32x4*)(outp + (size_t)rg * DFF) = o; }
	v_fmamk_f32 v34, v206, 0x3a800000, v159
	v_rsq_f32_e32 v34, v34
	s_nop 0
	v_pk_mul_f32 v[28:29], v[28:29], v[34:35] op_sel_hi:[1,0]
	v_pk_mul_f32 v[32:33], v[32:33], v[34:35] op_sel_hi:[1,0]
	v_pk_mul_f32 v[30:31], v[30:31], v[34:35] op_sel_hi:[1,0]
	v_pk_mul_f32 v[26:27], v[26:27], v[34:35] op_sel_hi:[1,0]
	v_mul_f32_e32 v43, 0xbfb8aa3b, v29
	v_pk_mul_f32 v[24:25], v[24:25], v[34:35] op_sel_hi:[1,0]
	v_pk_mul_f32 v[22:23], v[22:23], v[34:35] op_sel_hi:[1,0]
	v_pk_mul_f32 v[20:21], v[20:21], v[34:35] op_sel_hi:[1,0]
	v_pk_mul_f32 v[18:19], v[18:19], v[34:35] op_sel_hi:[1,0]
	v_mul_f32_e32 v34, 0xbfb8aa3b, v30
	v_mul_f32_e32 v35, 0xbfb8aa3b, v31
	v_mul_f32_e32 v38, 0xbfb8aa3b, v32
	v_mul_f32_e32 v39, 0xbfb8aa3b, v33
	v_mul_f32_e32 v40, 0xbfb8aa3b, v26
	v_mul_f32_e32 v41, 0xbfb8aa3b, v27
	v_mul_f32_e32 v42, 0xbfb8aa3b, v28
	v_exp_f32_e32 v43, v43
	v_exp_f32_e32 v34, v34
	v_exp_f32_e32 v35, v35
	v_exp_f32_e32 v38, v38
	v_exp_f32_e32 v39, v39
	v_exp_f32_e32 v40, v40
	v_exp_f32_e32 v41, v41
	v_exp_f32_e32 v42, v42
	v_add_f32_e32 v43, 1.0, v43
	v_add_f32_e32 v34, 1.0, v34
	v_add_f32_e32 v35, 1.0, v35
	v_add_f32_e32 v38, 1.0, v38
	v_add_f32_e32 v39, 1.0, v39
	v_add_f32_e32 v40, 1.0, v40
	v_add_f32_e32 v41, 1.0, v41
	v_add_f32_e32 v42, 1.0, v42
	v_rcp_f32_e32 v43, v43
	v_rcp_f32_e32 v34, v34
	v_rcp_f32_e32 v35, v35
	v_rcp_f32_e32 v38, v38
	v_rcp_f32_e32 v39, v39
	v_rcp_f32_e32 v40, v40
	v_rcp_f32_e32 v41, v41
	v_rcp_f32_e32 v42, v42
	v_mul_f32_e32 v29, v29, v43
	v_mul_f32_e32 v30, v30, v34
	v_mul_f32_e32 v31, v31, v35
	v_mul_f32_e32 v32, v32, v38
	v_mul_f32_e32 v33, v33, v39
	v_mul_f32_e32 v26, v26, v40
	v_mul_f32_e32 v27, v27, v41
	v_mul_f32_e32 v28, v28, v42
	v_mul_f32_e32 v21, v21, v29
	v_mul_f32_e32 v22, v22, v30
	v_mul_f32_e32 v23, v23, v31
	v_mul_f32_e32 v24, v24, v32
	v_mul_f32_e32 v25, v25, v33
	v_mul_f32_e32 v26, v18, v26
	v_mul_f32_e32 v27, v19, v27
	v_mul_f32_e32 v28, v20, v28
	v_cvt_pk_bf16_f32 v18, v22, v23
	v_cvt_pk_bf16_f32 v19, v24, v25
	v_cvt_pk_bf16_f32 v20, v26, v27
	v_cvt_pk_bf16_f32 v21, v28, v21
	ds_write_b128 v160, v[18:21]
	ds_read_b128 v[18:21], v161
	v_add_co_u32_e32 v22, vcc, s62, v114
	s_nop 1
	v_addc_co_u32_e32 v23, vcc, 0, v115, vcc
	s_waitcnt lgkmcnt(0)
	global_store_dwordx4 v[22:23], v[18:21], off
	s_nop 1
	v_add_co_u32_e32 v20, vcc, 0xf2000, v114
	s_waitcnt vmcnt(7)
	v_fmamk_f32 v18, v207, 0x3a800000, v159
	v_rsq_f32_e32 v18, v18
	s_nop 0
	v_pk_mul_f32 v[12:13], v[12:13], v[18:19] op_sel_hi:[1,0]
	v_pk_mul_f32 v[16:17], v[16:17], v[18:19] op_sel_hi:[1,0]
	v_pk_mul_f32 v[14:15], v[14:15], v[18:19] op_sel_hi:[1,0]
	v_pk_mul_f32 v[10:11], v[10:11], v[18:19] op_sel_hi:[1,0]
	v_mul_f32_e32 v26, 0xbfb8aa3b, v13
	v_pk_mul_f32 v[8:9], v[8:9], v[18:19] op_sel_hi:[1,0]
	v_pk_mul_f32 v[6:7], v[6:7], v[18:19] op_sel_hi:[1,0]
	v_pk_mul_f32 v[4:5], v[4:5], v[18:19] op_sel_hi:[1,0]
	v_pk_mul_f32 v[2:3], v[2:3], v[18:19] op_sel_hi:[1,0]
	v_mul_f32_e32 v18, 0xbfb8aa3b, v14
	v_mul_f32_e32 v19, 0xbfb8aa3b, v15
	v_mul_f32_e32 v21, 0xbfb8aa3b, v16
	v_mul_f32_e32 v22, 0xbfb8aa3b, v17
	v_mul_f32_e32 v23, 0xbfb8aa3b, v10
	v_mul_f32_e32 v24, 0xbfb8aa3b, v11
	v_mul_f32_e32 v25, 0xbfb8aa3b, v12
	v_exp_f32_e32 v26, v26
	v_exp_f32_e32 v18, v18
	v_exp_f32_e32 v19, v19
	v_exp_f32_e32 v21, v21
	v_exp_f32_e32 v22, v22
	v_exp_f32_e32 v23, v23
	v_exp_f32_e32 v24, v24
	v_exp_f32_e32 v25, v25
	v_add_f32_e32 v26, 1.0, v26
	v_add_f32_e32 v18, 1.0, v18
	v_add_f32_e32 v19, 1.0, v19
	v_add_f32_e32 v21, 1.0, v21
	v_add_f32_e32 v22, 1.0, v22
	v_add_f32_e32 v23, 1.0, v23
	v_add_f32_e32 v24, 1.0, v24
	v_add_f32_e32 v25, 1.0, v25
	v_rcp_f32_e32 v26, v26
	v_rcp_f32_e32 v18, v18
	v_rcp_f32_e32 v19, v19
	v_rcp_f32_e32 v21, v21
	v_rcp_f32_e32 v22, v22
	v_rcp_f32_e32 v23, v23
	v_rcp_f32_e32 v24, v24
	v_rcp_f32_e32 v25, v25
	v_mul_f32_e32 v13, v13, v26
	v_mul_f32_e32 v14, v14, v18
	v_mul_f32_e32 v15, v15, v19
	v_mul_f32_e32 v16, v16, v21
	v_mul_f32_e32 v17, v17, v22
	v_mul_f32_e32 v10, v10, v23
	v_mul_f32_e32 v11, v11, v24
	v_mul_f32_e32 v12, v12, v25
	v_mul_f32_e32 v5, v5, v13
	v_mul_f32_e32 v6, v6, v14
	v_mul_f32_e32 v7, v7, v15
	v_mul_f32_e32 v8, v8, v16
	v_mul_f32_e32 v9, v9, v17
	v_mul_f32_e32 v10, v2, v10
	v_mul_f32_e32 v11, v3, v11
	v_mul_f32_e32 v12, v4, v12
	v_cvt_pk_bf16_f32 v2, v6, v7
	v_cvt_pk_bf16_f32 v3, v8, v9
	v_cvt_pk_bf16_f32 v4, v10, v11
	v_cvt_pk_bf16_f32 v5, v12, v5
	ds_write_b128 v162, v[2:5]
	ds_read_b128 v[2:5], v163
	v_addc_co_u32_e32 v21, vcc, 0, v115, vcc
	s_andn2_b64 vcc, exec, s[0:1]
	s_mov_b64 s[0:1], -1
	s_waitcnt lgkmcnt(0)
	global_store_dwordx4 v[20:21], v[2:5], off
	s_cbranch_vccnz .LBB0_873
	s_andn2_b64 vcc, exec, s[12:13]
	s_cbranch_vccnz .LBB0_872
	s_barrier
	s_branch .LBB0_872
